# workspace pointer read once at kernel start and kept in VGPR lanes instead of a kernarg scalar load at every phase
# baseline (speedup 1.0000x reference)
.LBB0_6:
	v_readlane_b32 s0, v254, 1
	v_readlane_b32 s1, v254, 2
	s_add_u32 s80, s0, 0xf8
	s_addc_u32 s81, s1, 0
	s_cmp_lt_i32 s55, 0
	s_cselect_b64 s[0:1], -1, 0
	v_writelane_b32 v254, s0, 5
	v_lshrrev_b32_e32 v1, 20, v0
	v_lshrrev_b32_e32 v0, 10, v0
	v_writelane_b32 v254, s1, 6
	s_add_u32 s0, s52, 0x200
	s_addc_u32 s1, s53, 0
	v_writelane_b32 v254, s0, 7
	v_or_b32_e32 v0, v0, v1
	s_movk_i32 s97, 0x3ff
	v_writelane_b32 v254, s1, 8
	s_add_u32 s0, s52, 0x1000
	s_addc_u32 s1, s53, 0
	v_writelane_b32 v254, s0, 9
	v_and_or_b32 v0, v0, s97, v156
	v_mov_b32_e32 v145, 0
	v_writelane_b32 v254, s1, 10
	s_add_u32 s0, s52, 0x1100
	s_addc_u32 s1, s53, 0
	v_writelane_b32 v254, s0, 11
	v_mbcnt_lo_u32_b32 v1, -1, 0
	v_mbcnt_hi_u32_b32 v162, -1, v1
	v_writelane_b32 v254, s1, 12
	s_add_u32 s0, s52, 0x1200
	s_addc_u32 s1, s53, 0
	v_writelane_b32 v254, s0, 13
	v_and_b32_e32 v1, 64, v162
	s_movk_i32 s64, 0x1000
	v_writelane_b32 v254, s1, 14
	s_add_u32 s0, s52, 0x1300
	s_addc_u32 s1, s53, 0
	v_writelane_b32 v254, s0, 15
	s_cmp_eq_u32 s4, 15
	s_mov_b32 s93, 0x8000
	v_writelane_b32 v254, s1, 16
	s_cselect_b64 s[0:1], -1, 0
	v_writelane_b32 v254, s0, 17
	s_cmp_eq_u32 s4, 14
	v_mov_b32_e32 v157, 0x260
	v_writelane_b32 v254, s1, 18
	s_cselect_b64 s[0:1], -1, 0
	v_writelane_b32 v254, s0, 19
	s_cmp_eq_u32 s4, 13
	v_mov_b32_e32 v158, 0x358637bd
	v_writelane_b32 v254, s1, 20
	s_cselect_b64 s[0:1], -1, 0
	v_writelane_b32 v254, s0, 21
	s_cmp_eq_u32 s4, 12
	v_mov_b32_e32 v159, 0x3c0881c4
	v_writelane_b32 v254, s1, 22
	s_cselect_b64 s[0:1], -1, 0
	v_writelane_b32 v254, s0, 23
	s_cmp_eq_u32 s4, 11
	v_mov_b32_e32 v160, 0xbab64f3b
	v_writelane_b32 v254, s1, 24
	s_cselect_b64 s[0:1], -1, 0
	v_writelane_b32 v254, s0, 25
	s_cmp_eq_u32 s4, 10
	v_mov_b32_e32 v146, 1.0
	v_writelane_b32 v254, s1, 26
	s_cselect_b64 s[0:1], -1, 0
	v_writelane_b32 v254, s0, 27
	s_cmp_eq_u32 s4, 9
	v_mov_b32_e32 v161, 1
	v_writelane_b32 v254, s1, 28
	s_cselect_b64 s[0:1], -1, 0
	v_writelane_b32 v254, s0, 29
	s_cmp_eq_u32 s4, 8
	v_xor_b32_e32 v163, 16, v162
	v_writelane_b32 v254, s1, 30
	s_cselect_b64 s[0:1], -1, 0
	v_writelane_b32 v254, s0, 31
	s_cmp_eq_u32 s4, 7
	v_add_u32_e32 v164, 64, v1
	v_writelane_b32 v254, s1, 32
	s_cselect_b64 s[0:1], -1, 0
	v_writelane_b32 v254, s0, 33
	s_cmp_eq_u32 s4, 6
	v_xor_b32_e32 v165, 32, v162
	v_writelane_b32 v254, s1, 34
	s_cselect_b64 s[0:1], -1, 0
	v_writelane_b32 v254, s0, 35
	s_cmp_eq_u32 s4, 5
	v_mov_b32_e32 v166, 0x600
	v_writelane_b32 v254, s1, 36
	s_cselect_b64 s[0:1], -1, 0
	v_writelane_b32 v254, s0, 37
	s_cmp_eq_u32 s4, 4
	v_mov_b32_e32 v167, 0x1800000
	v_writelane_b32 v254, s1, 38
	s_cselect_b64 s[0:1], -1, 0
	v_writelane_b32 v254, s0, 39
	s_cmp_eq_u32 s4, 3
	v_mov_b32_e32 v168, 0x80
	v_writelane_b32 v254, s1, 40
	s_cselect_b64 s[0:1], -1, 0
	v_writelane_b32 v254, s0, 41
	s_cmp_eq_u32 s4, 2
	v_mov_b32_e32 v169, 0x7f800000
	v_writelane_b32 v254, s1, 42
	s_cselect_b64 s[0:1], -1, 0
	v_writelane_b32 v254, s0, 43
	s_cmp_eq_u32 s4, 1
	v_not_b32_e32 v170, 63
	v_writelane_b32 v254, s1, 44
	s_cselect_b64 s[0:1], -1, 0
	v_writelane_b32 v254, s0, 45
	s_cmp_eq_u32 s4, 0
	v_not_b32_e32 v171, 31
	v_writelane_b32 v254, s1, 46
	s_cselect_b64 s[0:1], -1, 0
	v_writelane_b32 v254, s0, 47
	v_mov_b32_e32 v172, 0x7fc00000
	s_movk_i32 s82, 0x11ff
	v_writelane_b32 v254, s1, 48
	s_lshl_b32 s0, s4, 8
	s_add_u32 s0, s52, s0
	s_addc_u32 s1, s53, 0
	s_add_u32 s2, s0, 0x1400
	s_addc_u32 s3, s1, 0
	v_writelane_b32 v254, s2, 49
	s_add_u32 s0, s0, 0x2400
	s_addc_u32 s1, s1, 0
	v_writelane_b32 v254, s3, 50
	v_writelane_b32 v254, s0, 51
	s_mov_b32 s83, 0xffac0000
	s_mov_b32 s34, 0xffb80000
	v_writelane_b32 v254, s1, 52
	s_add_u32 s0, s52, 0x3400
	s_addc_u32 s1, s53, 0
	v_writelane_b32 v254, s0, 53
	s_mov_b32 s35, 0xffc40000
	s_mov_b32 s88, 0xffd00000
	v_writelane_b32 v254, s1, 54
	s_add_u32 s0, s52, 0x3500
	s_addc_u32 s1, s53, 0
	v_writelane_b32 v254, s0, 55
	s_add_i32 s62, 0, 0x1c000
	s_mov_b32 s89, 0xffdc0000
	v_writelane_b32 v254, s1, 56
	s_add_i32 s0, 0, 0x4400
	v_writelane_b32 v254, s0, 57
	s_add_i32 s0, 0, 0x25000
	v_writelane_b32 v254, s0, 58
	s_add_i32 s0, 0, 0x25004
	v_writelane_b32 v254, s0, 59
	v_cmp_eq_u32_e64 s[0:1], 0, v0
	s_mov_b32 s65, 0xffe80000
	s_mov_b32 s60, 0xfff40000
	v_writelane_b32 v254, s0, 60
	s_movk_i32 s61, 0x2ff
	s_mov_b32 s85, 0
	v_writelane_b32 v254, s1, 61
	v_writelane_b32 v254, s80, 62
	s_mov_b64 s[86:87], 0x80
	s_mov_b32 s96, 0x3fd744fd
	s_mov_b64 s[6:7], 0xdce0080
	s_mov_b64 s[8:9], 0x1004100
	s_mov_b64 s[10:11], 0xdca0100
	s_mov_b64 s[12:13], 0x1044100
	s_mov_b64 s[14:15], 0xdce0100
	s_mov_b64 s[16:17], 0x1004180
	s_mov_b64 s[18:19], 0xdca0180
	s_mov_b64 s[20:21], 0x1044180
	s_mov_b64 s[22:23], 0x100
	s_mov_b64 s[36:37], 0x1284100
	s_mov_b64 s[78:79], 0x12c4100
	s_mov_b64 s[74:75], 0x1284180
	s_mov_b64 s[38:39], 0x12c4180
	s_mov_b64 s[26:27], 0x600000
	s_mov_b64 s[2:3], 0x1a04100
	s_mov_b64 s[66:67], 0x1a44100
	s_mov_b64 s[68:69], 0x1a04180
	s_mov_b64 s[70:71], 0x1a44180
	v_writelane_b32 v254, s81, 63
	v_readlane_b32 s98, v254, 1
	v_readlane_b32 s99, v254, 2
	s_nop 3
	s_load_dwordx2 s[98:99], s[98:99], 0xe8
	s_waitcnt lgkmcnt(0)
	v_writelane_b32 v255, s98, 44
	v_writelane_b32 v255, s99, 45
	s_branch .LBB0_10

.LBB0_10:
	v_readlane_b32 s72, v254, 1
	v_readlane_b32 s73, v254, 2
	s_waitcnt lgkmcnt(0)
	v_readlane_b32 s48, v255, 44
	v_readlane_b32 s49, v255, 45
	s_cmp_lg_u32 s54, 0
	s_mov_b64 s[0:1], -1
	s_cbranch_scc1 .LBB0_11
	s_getpc_b64 s[98:99]
